# stick-breaking cumulative product: the lane^32 half-wave exchange done with v_permlane32_swap on the VALU instead of ds_bpermute LDS round trips (8 per key tile)
# speedup vs baseline: 1.0026x; 1.0026x over previous
; __device__ __forceinline__ void sb_cum(f32x16& p, const float (&om)[16], float& run, int hi) {
; #pragma unroll
;     for (int g = 3; g >= 0; --g) {
;         const float Go = (om[4 * g] * om[4 * g + 1]) * (om[4 * g + 2] * om[4 * g + 3]); const float Gp = __shfl_xor(Go, 32);
;         const float c3 = run * (hi == 0 ? Gp : 1.0f), c2 = c3 * om[4 * g + 3], c1 = c2 * om[4 * g + 2], c0 = c1 * om[4 * g + 1];
;         p[4 * g + 3] *= c3; p[4 * g + 2] *= c2; p[4 * g + 1] *= c1; p[4 * g] *= c0;
;         run *= Go * Gp;
;     }
; }
.LBB0_891:
	v_pk_mul_f32 v[218:219], v[194:195], v[192:193]
	s_nop 0
	v_mul_f32_e32 v3, v218, v219
	v_mov_b32_e32 v5, v3
	v_mov_b32_e32 v232, v3
	s_nop 1
	v_permlane32_swap_b32_e32 v5, v232
	v_cndmask_b32_e64 v5, v5, v232, s[4:5]
	v_pk_mul_f32 v[218:219], v[190:191], v[14:15]
	s_waitcnt lgkmcnt(0)
	v_cndmask_b32_e64 v7, 1.0, v5, s[4:5]
	v_mul_f32_e32 v9, v218, v219
	v_mul_f32_e32 v219, v189, v7
	v_mov_b32_e32 v220, v9
	v_mov_b32_e32 v232, v9
	s_nop 1
	v_permlane32_swap_b32_e32 v220, v232
	v_cndmask_b32_e64 v220, v220, v232, s[4:5]
	v_mul_f32_e32 v218, v194, v219
	v_mul_f32_e32 v193, v192, v218
	v_mul_f32_e32 v192, v195, v193
	v_pk_mul_f32 v[194:195], v[12:13], v[10:11]
	v_mul_f32_e32 v3, v3, v5
	v_pk_mul_f32 v[194:195], v[194:195], v[194:195] op_sel:[0,1] op_sel_hi:[1,0]
	v_mov_b32_e32 v7, v194
	v_mov_b32_e32 v232, v194
	s_nop 1
	v_permlane32_swap_b32_e32 v7, v232
	v_cndmask_b32_e64 v7, v7, v232, s[4:5]
	v_mul_f32_e32 v3, v189, v3
	s_waitcnt lgkmcnt(1)
	v_cndmask_b32_e64 v5, 1.0, v220, s[4:5]
	v_mul_f32_e32 v189, v3, v5
	v_mul_f32_e32 v188, v190, v189
	v_mul_f32_e32 v15, v14, v188
	v_mul_f32_e32 v5, v9, v220
	v_mov_b32_e32 v9, v194
	v_mul_f32_e32 v14, v191, v15
	v_pk_mul_f32 v[2:3], v[4:5], v[2:3]
	s_waitcnt lgkmcnt(0)
	v_pk_mul_f32 v[190:191], v[8:9], v[6:7]
	v_cndmask_b32_e64 v11, 1.0, v7, s[4:5]
	v_pk_mul_f32 v[190:191], v[190:191], v[2:3]
	v_mov_b32_e32 v7, v190
	v_mov_b32_e32 v232, v190
	s_nop 1
	v_permlane32_swap_b32_e32 v7, v232
	v_cndmask_b32_e64 v7, v7, v232, s[4:5]
	v_mul_f32_e32 v3, v3, v11
	v_mul_f32_e32 v2, v12, v3
	v_mul_f32_e32 v11, v10, v2
	v_mul_f32_e32 v10, v13, v11
	s_waitcnt lgkmcnt(0)
	v_cndmask_b32_e64 v5, 1.0, v7, s[4:5]
	v_mul_f32_e32 v9, v191, v5
	v_mul_f32_e32 v8, v8, v9
	v_mul_f32_e32 v5, v6, v8
	v_mul_f32_e32 v4, v4, v5
	v_pk_mul_f32 v[54:55], v[54:55], v[2:3]
	v_mul_f32_e32 v2, v190, v7
	v_pk_mul_f32 v[50:51], v[50:51], v[8:9]
	v_pk_mul_f32 v[48:49], v[48:49], v[4:5]
	v_pk_mul_f32 v[52:53], v[52:53], v[10:11]
	v_pk_mul_f32 v[58:59], v[58:59], v[188:189]
	v_pk_mul_f32 v[56:57], v[56:57], v[14:15]
	v_pk_mul_f32 v[62:63], v[62:63], v[218:219]
	v_pk_mul_f32 v[60:61], v[60:61], v[192:193]
	v_mul_f32_e32 v189, v2, v191

; #define MFMA32(a, b, c) __builtin_amdgcn_mfma_f32_32x32x16_bf16((a), (b), (c), 0, 0, 0)
; __device__ __forceinline__ void sb_cum(f32x16& p, const float (&om)[16], float& run, int hi) {
; #pragma unroll
;     for (int g = 3; g >= 0; --g) {
;         const float Go = (om[4 * g] * om[4 * g + 1]) * (om[4 * g + 2] * om[4 * g + 3]); const float Gp = __shfl_xor(Go, 32);
;         const float c3 = run * (hi == 0 ? Gp : 1.0f), c2 = c3 * om[4 * g + 3], c1 = c2 * om[4 * g + 2], c0 = c1 * om[4 * g + 1];
;         p[4 * g + 3] *= c3; p[4 * g + 2] *= c2; p[4 * g + 1] *= c1; p[4 * g] *= c0;
;         run *= Go * Gp;
;     }
; }
; __device__ __forceinline__ void sb_unit(const Args& a, int l, int u, LAS unsigned char* wl, int lane) {
;     ...
;         bf16x8 pa[4];
;         { u32x4 w;
;           w.x = cvtpk(p0[0], p0[1]); w.y = cvtpk(p0[2], p0[3]); w.z = cvtpk(p0[4], p0[5]); w.w = cvtpk(p0[6], p0[7]); pa[0] = __builtin_bit_cast(bf16x8, w);
;           w.x = cvtpk(p0[8], p0[9]); w.y = cvtpk(p0[10], p0[11]); w.z = cvtpk(p0[12], p0[13]); w.w = cvtpk(p0[14], p0[15]); pa[1] = __builtin_bit_cast(bf16x8, w);
;           w.x = cvtpk(p1[0], p1[1]); w.y = cvtpk(p1[2], p1[3]); w.z = cvtpk(p1[4], p1[5]); w.w = cvtpk(p1[6], p1[7]); pa[2] = __builtin_bit_cast(bf16x8, w);
;           w.x = cvtpk(p1[8], p1[9]); w.y = cvtpk(p1[10], p1[11]); w.z = cvtpk(p1[12], p1[13]); w.w = cvtpk(p1[14], p1[15]); pa[3] = __builtin_bit_cast(bf16x8, w); }
;         asm volatile("s_waitcnt lgkmcnt(0)" ::: "memory");
; #pragma unroll
;         for (int d0 = 0; d0 < 2; ++d0)
; #pragma unroll
;             for (int ks = 0; ks < 2; ++ks) {
;                 const s16x4 lo = vtr(vp + d0 * 4096 + ks * 1024), hh = vtr(vp + d0 * 4096 + ks * 1024 + 512);
;                 const bf16x8 vf = (bf16x8){lo[0], lo[1], lo[2], lo[3], hh[0], hh[1], hh[2], hh[3]};
;                 o[d0] = MFMA32(pa[ks], vf, o[d0]);
;             }
;         if (!skip1) {
; #pragma unroll
;             for (int d0 = 0; d0 < 2; ++d0)
; #pragma unroll
;                 for (int ks = 2; ks < 4; ++ks) {
;                     const s16x4 lo = vtr(vp + d0 * 4096 + ks * 1024), hh = vtr(vp + d0 * 4096 + ks * 1024 + 512);
;                     const bf16x8 vf = (bf16x8){lo[0], lo[1], lo[2], lo[3], hh[0], hh[1], hh[2], hh[3]};
;                     o[d0] = MFMA32(pa[ks], vf, o[d0]);
;                 }
;         }
.LBB0_896:
	v_pk_mul_f32 v[192:193], v[74:75], v[72:73]
	s_waitcnt lgkmcnt(0)
	s_and_b64 vcc, exec, s[6:7]
	v_pk_mul_f32 v[192:193], v[192:193], v[192:193] op_sel:[0,1] op_sel_hi:[1,0]
	v_mov_b32_e32 v73, v192
	v_mov_b32_e32 v232, v192
	s_nop 1
	v_permlane32_swap_b32_e32 v73, v232
	v_cndmask_b32_e64 v73, v73, v232, s[4:5]
	s_waitcnt lgkmcnt(0)
	v_cndmask_b32_e64 v0, 1.0, v73, s[4:5]
	v_mul_f32_e32 v195, v189, v0
	v_mul_f32_e32 v194, v74, v195
	v_pk_mul_f32 v[70:71], v[70:71], v[194:195]
	v_mul_f32_e32 v195, v72, v194
	v_mul_f32_e32 v194, v75, v195
	v_pk_mul_f32 v[74:75], v[76:77], v[194:195]
	v_pk_mul_f32 v[76:77], v[66:67], v[64:65]
	v_mov_b32_e32 v195, v192
	v_mov_b32_e32 v194, v76
	v_mov_b32_e32 v72, v77
	v_pk_mul_f32 v[72:73], v[194:195], v[72:73]
	v_mov_b32_e32 v188, v72
	v_mov_b32_e32 v232, v72
	s_nop 1
	v_permlane32_swap_b32_e32 v188, v232
	v_cndmask_b32_e64 v188, v188, v232, s[4:5]
	s_waitcnt lgkmcnt(0)
	v_cndmask_b32_e64 v0, 1.0, v188, s[4:5]
	v_pk_mul_f32 v[72:73], v[72:73], v[188:189]
	s_nop 0
	v_mul_f32_e32 v77, v73, v0
	v_mul_f32_e32 v76, v66, v77
	v_mul_f32_e32 v65, v64, v76
	v_mul_f32_e32 v64, v67, v65
	v_pk_mul_f32 v[66:67], v[10:11], v[6:7]
	v_pk_mul_f32 v[64:65], v[68:69], v[64:65]
	v_mov_b32_e32 v68, v66
	v_mov_b32_e32 v69, v72
	v_mov_b32_e32 v72, v67
	v_pk_mul_f32 v[66:67], v[68:69], v[72:73]
	v_mov_b32_e32 v0, v66
	v_mov_b32_e32 v232, v66
	s_nop 1
	v_permlane32_swap_b32_e32 v0, v232
	v_cndmask_b32_e64 v0, v0, v232, s[4:5]
	v_pk_mul_f32 v[14:15], v[14:15], v[76:77]
	s_waitcnt lgkmcnt(0)
	v_cndmask_b32_e64 v7, 1.0, v0, s[4:5]
	v_mul_f32_e32 v69, v67, v7
	v_mul_f32_e32 v68, v10, v69
	v_mul_f32_e32 v7, v6, v68
	v_mul_f32_e32 v6, v11, v7
	v_pk_mul_f32 v[10:11], v[12:13], v[6:7]
	v_mul_f32_e32 v6, v78, v191
	v_mul_f32_e32 v7, v190, v79
	v_mul_f32_e32 v6, v7, v6
	v_mov_b32_e32 v7, v6
	v_mov_b32_e32 v232, v6
	s_nop 1
	v_permlane32_swap_b32_e32 v7, v232
	v_cndmask_b32_e64 v7, v7, v232, s[4:5]
	v_mul_f32_e32 v0, v66, v0
	v_mul_f32_e32 v0, v0, v67
	v_pk_mul_f32 v[8:9], v[8:9], v[68:69]
	s_waitcnt lgkmcnt(0)
	v_cndmask_b32_e64 v12, 1.0, v7, s[4:5]
	v_mul_f32_e32 v13, v0, v12
	v_mul_f32_e32 v12, v190, v13
	v_pk_mul_f32 v[4:5], v[4:5], v[12:13]
	v_mul_f32_e32 v13, v79, v12
	v_mul_f32_e32 v12, v78, v13
	v_pk_mul_f32 v[2:3], v[2:3], v[12:13]
	s_nop 0
	v_cvt_pk_bf16_f32 v2, v2, v3
	v_cvt_pk_bf16_f32 v3, v4, v5
	v_cvt_pk_bf16_f32 v4, v10, v11
	v_cvt_pk_bf16_f32 v5, v8, v9
	v_cvt_pk_bf16_f32 v9, v14, v15
	ds_read_b64_tr_b16 v[12:13], v214
	ds_read_b64_tr_b16 v[14:15], v214 offset:512
	s_waitcnt lgkmcnt(0)
	v_mfma_f32_32x32x16_bf16 v[32:47], v[2:5], v[12:15], v[32:47]
	v_cvt_pk_bf16_f32 v8, v64, v65
	v_cvt_pk_bf16_f32 v10, v74, v75
	v_cvt_pk_bf16_f32 v11, v70, v71
	ds_read_b64_tr_b16 v[12:13], v214 offset:1024
	ds_read_b64_tr_b16 v[14:15], v214 offset:1536
	s_waitcnt lgkmcnt(0)
	v_mfma_f32_32x32x16_bf16 v[32:47], v[8:11], v[12:15], v[32:47]
	ds_read_b64_tr_b16 v[12:13], v214 offset:4096
	ds_read_b64_tr_b16 v[14:15], v214 offset:4608
	s_waitcnt lgkmcnt(0)
	v_mfma_f32_32x32x16_bf16 v[16:31], v[2:5], v[12:15], v[16:31]
	ds_read_b64_tr_b16 v[2:3], v214 offset:5120
	ds_read_b64_tr_b16 v[4:5], v214 offset:5632
	s_waitcnt lgkmcnt(0)
	v_mfma_f32_32x32x16_bf16 v[16:31], v[8:11], v[2:5], v[16:31]
	s_cbranch_vccnz .LBB0_898
	v_cvt_pk_bf16_f32 v8, v48, v49
	v_cvt_pk_bf16_f32 v9, v50, v51
	v_cvt_pk_bf16_f32 v10, v52, v53
	v_cvt_pk_bf16_f32 v11, v54, v55
	ds_read_b64_tr_b16 v[12:13], v214 offset:2048
	ds_read_b64_tr_b16 v[14:15], v214 offset:2560
	s_waitcnt lgkmcnt(0)
	v_mfma_f32_32x32x16_bf16 v[32:47], v[8:11], v[12:15], v[32:47]
	v_cvt_pk_bf16_f32 v2, v56, v57
	v_cvt_pk_bf16_f32 v3, v58, v59
	v_cvt_pk_bf16_f32 v4, v60, v61
	v_cvt_pk_bf16_f32 v5, v62, v63
	ds_read_b64_tr_b16 v[12:13], v214 offset:3072
	ds_read_b64_tr_b16 v[14:15], v214 offset:3584
	s_waitcnt lgkmcnt(0)
	v_mfma_f32_32x32x16_bf16 v[32:47], v[2:5], v[12:15], v[32:47]
	ds_read_b64_tr_b16 v[12:13], v214 offset:6144
	ds_read_b64_tr_b16 v[14:15], v214 offset:6656
	s_waitcnt lgkmcnt(0)
	v_mfma_f32_32x32x16_bf16 v[16:31], v[8:11], v[12:15], v[16:31]
	ds_read_b64_tr_b16 v[8:9], v214 offset:7168
	ds_read_b64_tr_b16 v[10:11], v214 offset:7680
	s_waitcnt lgkmcnt(0)
	v_mfma_f32_32x32x16_bf16 v[16:31], v[2:5], v[8:11], v[16:31]
